# MoE-down GEMM K-loop converted to direct global->LDS loads (LDS-DMA): unpadded XOR-swizzled LDS image, swizzle on source chunk, M0 per 1KB piece, no ds_write / staging VGPRs
# speedup vs baseline: 1.0285x; 1.0118x over previous
.LBB0_946:
	s_ashr_i32 s2, s19, 3
	s_and_b32 s3, s2, -8
	s_and_b32 s12, s19, 7
	s_or_b32 s3, s3, s12
	s_cmp_ge_i32 s3, s17
	s_cbranch_scc1 .LBB0_945
	v_mov_b32_e32 v129, v216
	s_lshl_b32 s20, s3, 7
	s_lshl_b32 s3, s19, 4
	s_and_b32 s21, s3, 0x380
	v_ashrrev_i32_e32 v15, 3, v129
	v_add_u32_e32 v0, s20, v15
	v_lshlrev_b32_e32 v1, 4, v129
	v_and_b32_e32 v128, 0x70, v1
	v_add_u32_e32 v1, s21, v15
	v_mul_lo_u32 v0, v0, s88
	v_or_b32_e32 v16, v0, v128
	v_mul_lo_u32 v0, v1, s88
	v_or_b32_e32 v17, v0, v128
	v_add_u32_e32 v18, 0x38000, v16
	v_add_u32_e32 v19, 0x38000, v17
	v_add_u32_e32 v20, 0x70000, v16
	v_add_u32_e32 v21, 0x70000, v17
	v_add_u32_e32 v22, 0xa8000, v16
	v_add_u32_e32 v23, 0xa8000, v17
	s_bfe_u32 s3, s18, 0x30007
	s_and_b32 s12, s15, 7
	s_lshl_b32 s2, s2, 7
	s_mul_i32 s13, s3, 0xe0000
	s_lshl_b32 s3, s12, 7
	s_and_b32 s2, s2, 0x3ffc00
	v_ashrrev_i32_e32 v16, 1, v129
	v_and_b32_e32 v134, 31, v129
	v_lshrrev_b32_e32 v17, 1, v129
	v_and_b32_e32 v18, 0x5f, v129
	s_or_b32 s2, s3, s2
	v_and_b32_e32 v135, 0xffffffc0, v16
	v_and_b32_e32 v16, 16, v17
	v_mul_u32_u24_e32 v17, 0x48, v18
	v_mul_lo_u32 v18, v15, s88
	v_add_u32_e32 v19, s2, v15
	v_mad_u64_u32 v[130:131], s[2:3], v15, s97, v[128:129]
	v_or_b32_e32 v15, v135, v134
	v_mov_b32_e32 v0, 0
	v_mad_u64_u32 v[132:133], s[2:3], v15, s97, v[16:17]
	s_mov_b32 s22, 0
	v_mov_b32_e32 v1, v0
	v_mov_b32_e32 v2, v0
	v_mov_b32_e32 v3, v0
	v_mov_b32_e32 v4, v0
	v_mov_b32_e32 v5, v0
	v_mov_b32_e32 v6, v0
	v_mov_b32_e32 v7, v0
	v_mov_b32_e32 v8, v0
	v_mov_b32_e32 v9, v0
	v_mov_b32_e32 v10, v0
	v_mov_b32_e32 v11, v0
	v_mov_b32_e32 v12, v0
	v_mov_b32_e32 v13, v0
	v_mov_b32_e32 v14, v0
	v_lshl_add_u32 v131, v17, 1, v16
	v_add_u32_e32 v136, s13, v18
	v_mul_lo_u32 v137, v19, s88
	v_add_u32_e32 v133, 0xd800, v130
	v_mov_b32_e32 v15, v0
	v_mov_b32_e32 v32, v0
	v_mov_b32_e32 v33, v0
	v_mov_b32_e32 v34, v0
	v_mov_b32_e32 v35, v0
	v_mov_b32_e32 v36, v0
	v_mov_b32_e32 v37, v0
	v_mov_b32_e32 v38, v0
	v_mov_b32_e32 v39, v0
	v_mov_b32_e32 v40, v0
	v_mov_b32_e32 v41, v0
	v_mov_b32_e32 v42, v0
	v_mov_b32_e32 v43, v0
	v_mov_b32_e32 v44, v0
	v_mov_b32_e32 v45, v0
	v_mov_b32_e32 v46, v0
	v_mov_b32_e32 v47, v0
	v_mov_b32_e32 v16, v0
	v_mov_b32_e32 v17, v0
	v_mov_b32_e32 v18, v0
	v_mov_b32_e32 v19, v0
	v_mov_b32_e32 v20, v0
	v_mov_b32_e32 v21, v0
	v_mov_b32_e32 v22, v0
	v_mov_b32_e32 v23, v0
	v_mov_b32_e32 v24, v0
	v_mov_b32_e32 v25, v0
	v_mov_b32_e32 v26, v0
	v_mov_b32_e32 v27, v0
	v_mov_b32_e32 v28, v0
	v_mov_b32_e32 v29, v0
	v_mov_b32_e32 v30, v0
	v_mov_b32_e32 v31, v0
	v_mov_b32_e32 v48, v0
	v_mov_b32_e32 v49, v0
	v_mov_b32_e32 v50, v0
	v_mov_b32_e32 v51, v0
	v_mov_b32_e32 v52, v0
	v_mov_b32_e32 v53, v0
	v_mov_b32_e32 v54, v0
	v_mov_b32_e32 v55, v0
	v_mov_b32_e32 v56, v0
	v_mov_b32_e32 v57, v0
	v_mov_b32_e32 v58, v0
	v_mov_b32_e32 v59, v0
	v_mov_b32_e32 v60, v0
	v_mov_b32_e32 v61, v0
	v_mov_b32_e32 v62, v0
	v_mov_b32_e32 v63, v0
	v_and_b32_e32 v75, 7, v216
	v_bfe_u32 v76, v216, 4, 3
	v_xor_b32_e32 v75, v75, v76
	v_lshlrev_b32_e32 v75, 4, v75
	v_add_u32_e32 v72, v75, v137
	v_add_u32_e32 v73, v75, v136
	v_lshrrev_b32_e32 v76, 6, v216
	v_lshlrev_b32_e32 v77, 10, v76
	v_and_b32_e32 v78, 31, v216
	v_bfe_u32 v79, v216, 5, 1
	v_readfirstlane_b32 s12, v77
	v_bfe_u32 v80, v78, 1, 3
	v_lshrrev_b32_e32 v81, 1, v76
	v_and_b32_e32 v82, 1, v76
	v_lshl_add_u32 v81, v81, 6, v78
	v_lshl_add_u32 v82, v82, 6, v78
	v_lshlrev_b32_e32 v81, 7, v81
	v_lshlrev_b32_e32 v82, 7, v82
	v_add_u32_e32 v82, 0x8000, v82
	v_or_b32_e32 v83, 0, v79
	v_xor_b32_e32 v83, v83, v80
	v_lshl_add_u32 v64, v83, 4, v81
	v_lshl_add_u32 v68, v83, 4, v82
	v_or_b32_e32 v83, 2, v79
	v_xor_b32_e32 v83, v83, v80
	v_lshl_add_u32 v65, v83, 4, v81
	v_lshl_add_u32 v69, v83, 4, v82
	v_or_b32_e32 v83, 4, v79
	v_xor_b32_e32 v83, v83, v80
	v_lshl_add_u32 v66, v83, 4, v81
	v_lshl_add_u32 v70, v83, 4, v82
	v_or_b32_e32 v83, 6, v79
	v_xor_b32_e32 v83, v83, v80
	v_lshl_add_u32 v67, v83, 4, v81
	v_lshl_add_u32 v71, v83, 4, v82
	s_nop 0
	s_add_u32 m0, s12, 0x0
	v_add_u32_e32 v74, 0x0, v72
	global_load_lds_dwordx4 v74, s[8:9]
	s_add_u32 m0, s12, 0x8000
	v_add_u32_e32 v74, 0x0, v73
	global_load_lds_dwordx4 v74, s[10:11]
	s_add_u32 m0, s12, 0x1000
	v_add_u32_e32 v74, 0x38000, v72
	global_load_lds_dwordx4 v74, s[8:9]
	s_add_u32 m0, s12, 0x9000
	v_add_u32_e32 v74, 0x38000, v73
	global_load_lds_dwordx4 v74, s[10:11]
	s_add_u32 m0, s12, 0x2000
	v_add_u32_e32 v74, 0x70000, v72
	global_load_lds_dwordx4 v74, s[8:9]
	s_add_u32 m0, s12, 0xa000
	v_add_u32_e32 v74, 0x70000, v73
	global_load_lds_dwordx4 v74, s[10:11]
	s_add_u32 m0, s12, 0x3000
	v_add_u32_e32 v74, 0xa8000, v72
	global_load_lds_dwordx4 v74, s[8:9]
	s_add_u32 m0, s12, 0xb000
	v_add_u32_e32 v74, 0xa8000, v73
	global_load_lds_dwordx4 v74, s[10:11]
	s_waitcnt vmcnt(0)
	s_barrier
	s_mov_b32 s22, 0
.Ldma_loop:
	s_add_u32 m0, s12, 0x4000
	v_add_u32_e32 v74, 0x80, v72
	global_load_lds_dwordx4 v74, s[8:9]
	s_add_u32 m0, s12, 0xc000
	v_add_u32_e32 v74, 0x80, v73
	global_load_lds_dwordx4 v74, s[10:11]
	s_add_u32 m0, s12, 0x5000
	v_add_u32_e32 v74, 0x38080, v72
	global_load_lds_dwordx4 v74, s[8:9]
	s_add_u32 m0, s12, 0xd000
	v_add_u32_e32 v74, 0x38080, v73
	global_load_lds_dwordx4 v74, s[10:11]
	s_add_u32 m0, s12, 0x6000
	v_add_u32_e32 v74, 0x70080, v72
	global_load_lds_dwordx4 v74, s[8:9]
	s_add_u32 m0, s12, 0xe000
	v_add_u32_e32 v74, 0x70080, v73
	global_load_lds_dwordx4 v74, s[10:11]
	s_add_u32 m0, s12, 0x7000
	v_add_u32_e32 v74, 0xa8080, v72
	global_load_lds_dwordx4 v74, s[8:9]
	s_add_u32 m0, s12, 0xf000
	v_add_u32_e32 v74, 0xa8080, v73
	global_load_lds_dwordx4 v74, s[10:11]
	s_setprio 1
	ds_read_b128 v[144:147], v68 offset:4096
	ds_read_b128 v[140:143], v64 offset:4096
	s_waitcnt lgkmcnt(0)
	v_mfma_f32_32x32x16_bf16 v[0:15], v[144:147], v[140:143], v[0:15]
	ds_read_b128 v[148:151], v64
	ds_read_b128 v[152:155], v65
	s_waitcnt lgkmcnt(1)
	v_mfma_f32_32x32x16_bf16 v[32:47], v[144:147], v[148:151], v[32:47]
	ds_read_b128 v[156:159], v68
	ds_read_b128 v[160:163], v69
	s_waitcnt lgkmcnt(1)
	v_mfma_f32_32x32x16_bf16 v[48:63], v[156:159], v[148:151], v[48:63]
	ds_read_b128 v[144:147], v69 offset:4096
	ds_read_b128 v[148:151], v70
	v_mfma_f32_32x32x16_bf16 v[16:31], v[156:159], v[140:143], v[16:31]
	ds_read_b128 v[140:143], v65 offset:4096
	s_waitcnt lgkmcnt(3)
	v_mfma_f32_32x32x16_bf16 v[48:63], v[160:163], v[152:155], v[48:63]
	s_waitcnt lgkmcnt(0)
	v_mfma_f32_32x32x16_bf16 v[16:31], v[160:163], v[140:143], v[16:31]
	v_mfma_f32_32x32x16_bf16 v[32:47], v[144:147], v[152:155], v[32:47]
	ds_read_b128 v[152:155], v70 offset:4096
	v_mfma_f32_32x32x16_bf16 v[0:15], v[144:147], v[140:143], v[0:15]
	ds_read_b128 v[140:143], v66
	ds_read_b128 v[144:147], v66 offset:4096
	s_waitcnt lgkmcnt(1)
	v_mfma_f32_32x32x16_bf16 v[48:63], v[148:151], v[140:143], v[48:63]
	s_waitcnt lgkmcnt(0)
	v_mfma_f32_32x32x16_bf16 v[16:31], v[148:151], v[144:147], v[16:31]
	ds_read_b128 v[148:151], v71
	v_mfma_f32_32x32x16_bf16 v[32:47], v[152:155], v[140:143], v[32:47]
	ds_read_b128 v[140:143], v67
	v_mfma_f32_32x32x16_bf16 v[0:15], v[152:155], v[144:147], v[0:15]
	ds_read_b128 v[152:155], v71 offset:4096
	ds_read_b128 v[144:147], v67 offset:4096
	s_waitcnt lgkmcnt(2)
	v_mfma_f32_32x32x16_bf16 v[48:63], v[148:151], v[140:143], v[48:63]
	s_waitcnt lgkmcnt(0)
	v_mfma_f32_32x32x16_bf16 v[16:31], v[148:151], v[144:147], v[16:31]
	v_mfma_f32_32x32x16_bf16 v[32:47], v[152:155], v[140:143], v[32:47]
	v_mfma_f32_32x32x16_bf16 v[0:15], v[152:155], v[144:147], v[0:15]
	s_setprio 0
	s_waitcnt vmcnt(0)
	s_barrier
	s_cmp_ge_u32 s22, 54
	s_cbranch_scc1 .Ldma_skip
	s_add_u32 m0, s12, 0x0
	v_add_u32_e32 v74, 0x100, v72
	global_load_lds_dwordx4 v74, s[8:9]
	s_add_u32 m0, s12, 0x8000
	v_add_u32_e32 v74, 0x100, v73
	global_load_lds_dwordx4 v74, s[10:11]
	s_add_u32 m0, s12, 0x1000
	v_add_u32_e32 v74, 0x38100, v72
	global_load_lds_dwordx4 v74, s[8:9]
	s_add_u32 m0, s12, 0x9000
	v_add_u32_e32 v74, 0x38100, v73
	global_load_lds_dwordx4 v74, s[10:11]
	s_add_u32 m0, s12, 0x2000
	v_add_u32_e32 v74, 0x70100, v72
	global_load_lds_dwordx4 v74, s[8:9]
	s_add_u32 m0, s12, 0xa000
	v_add_u32_e32 v74, 0x70100, v73
	global_load_lds_dwordx4 v74, s[10:11]
	s_add_u32 m0, s12, 0x3000
	v_add_u32_e32 v74, 0xa8100, v72
	global_load_lds_dwordx4 v74, s[8:9]
	s_add_u32 m0, s12, 0xb000
	v_add_u32_e32 v74, 0xa8100, v73
	global_load_lds_dwordx4 v74, s[10:11]
.Ldma_skip:
	s_setprio 1
	ds_read_b128 v[142:145], v68 offset:20480
	ds_read_b128 v[138:141], v64 offset:20480
	s_waitcnt lgkmcnt(0)
	v_mfma_f32_32x32x16_bf16 v[0:15], v[142:145], v[138:141], v[0:15]
	ds_read_b128 v[146:149], v64 offset:16384
	ds_read_b128 v[150:153], v65 offset:16384
	s_waitcnt lgkmcnt(1)
	v_mfma_f32_32x32x16_bf16 v[32:47], v[142:145], v[146:149], v[32:47]
	ds_read_b128 v[154:157], v68 offset:16384
	ds_read_b128 v[158:161], v69 offset:16384
	s_waitcnt lgkmcnt(1)
	v_mfma_f32_32x32x16_bf16 v[48:63], v[154:157], v[146:149], v[48:63]
	ds_read_b128 v[142:145], v69 offset:20480
	ds_read_b128 v[146:149], v70 offset:16384
	v_mfma_f32_32x32x16_bf16 v[16:31], v[154:157], v[138:141], v[16:31]
	ds_read_b128 v[138:141], v65 offset:20480
	s_waitcnt lgkmcnt(3)
	v_mfma_f32_32x32x16_bf16 v[48:63], v[158:161], v[150:153], v[48:63]
	s_waitcnt lgkmcnt(0)
	v_mfma_f32_32x32x16_bf16 v[16:31], v[158:161], v[138:141], v[16:31]
	v_mfma_f32_32x32x16_bf16 v[32:47], v[142:145], v[150:153], v[32:47]
	ds_read_b128 v[150:153], v70 offset:20480
	v_mfma_f32_32x32x16_bf16 v[0:15], v[142:145], v[138:141], v[0:15]
	ds_read_b128 v[138:141], v66 offset:16384
	ds_read_b128 v[142:145], v66 offset:20480
	s_waitcnt lgkmcnt(1)
	v_mfma_f32_32x32x16_bf16 v[48:63], v[146:149], v[138:141], v[48:63]
	s_waitcnt lgkmcnt(0)
	v_mfma_f32_32x32x16_bf16 v[16:31], v[146:149], v[142:145], v[16:31]
	ds_read_b128 v[146:149], v71 offset:16384
	v_mfma_f32_32x32x16_bf16 v[32:47], v[150:153], v[138:141], v[32:47]
	ds_read_b128 v[138:141], v67 offset:16384
	v_mfma_f32_32x32x16_bf16 v[0:15], v[150:153], v[142:145], v[0:15]
	ds_read_b128 v[150:153], v71 offset:20480
	ds_read_b128 v[142:145], v67 offset:20480
	s_waitcnt lgkmcnt(2)
	v_mfma_f32_32x32x16_bf16 v[48:63], v[146:149], v[138:141], v[48:63]
	s_waitcnt lgkmcnt(0)
	v_mfma_f32_32x32x16_bf16 v[16:31], v[146:149], v[142:145], v[16:31]
	v_mfma_f32_32x32x16_bf16 v[32:47], v[150:153], v[138:141], v[32:47]
	v_mfma_f32_32x32x16_bf16 v[0:15], v[150:153], v[142:145], v[0:15]
	s_setprio 0
	s_waitcnt vmcnt(0)
	s_barrier
	v_add_u32_e32 v72, 0x100, v72
	v_add_u32_e32 v73, 0x100, v73
	s_add_i32 s22, s22, 2
	s_cmp_lt_u32 s22, 56
	s_cbranch_scc1 .Ldma_loop
